# NA step loop: K/V tile loads issued two steps ahead (two staging register sets by step parity) on top of the ladder and in-place accumulators
# baseline (speedup 1.0000x reference)
.LBB0_1069:
	s_and_b32 s48, s45, 7
	s_lshl_b32 s49, s48, 2
	s_add_i32 s47, s49, s11
	v_or_b32_e32 v2, s47, v108
	v_lshl_add_u32 v0, v2, 6, v109
	s_ashr_i32 s30, s45, 7
	v_ashrrev_i32_e32 v1, 31, v0
	v_mad_i64_i32 v[102:103], s[12:13], s30, v130, v[0:1]
	v_readlane_b32 s72, v239, 32
	s_bfe_u32 s40, s45, 0x40003
	v_lshlrev_b64 v[0:1], 11, v[102:103]
	v_readlane_b32 s74, v239, 34
	v_readlane_b32 s75, v239, 35
	s_lshl_b32 s22, s40, 7
	s_lshl_b32 s46, s40, 6
	v_lshl_add_u64 v[0:1], s[74:75], 0, v[0:1]
	v_lshl_add_u64 v[0:1], v[0:1], 0, s[22:23]
	v_lshl_add_u64 v[0:1], v[0:1], 0, v[98:99]
	global_load_dwordx4 v[64:67], v[0:1], off
	global_load_dwordx4 v[68:71], v[0:1], off offset:32
	global_load_dwordx4 v[72:75], v[0:1], off offset:64
	global_load_dwordx4 v[76:79], v[0:1], off offset:96
	v_mad_i64_i32 v[0:1], s[12:13], s30, v130, v[92:93]
	s_mul_hi_i32 s13, s30, 0xfffffb00
	s_mulk_i32 s30, 0xfb00
	v_readlane_b32 s76, v239, 36
	v_readlane_b32 s77, v239, 37
	v_lshlrev_b64 v[4:5], 11, v[0:1]
	s_add_u32 s12, s46, s30
	v_lshl_add_u64 v[4:5], s[76:77], 0, v[4:5]
	s_addc_u32 s13, 0, s13
	v_lshl_add_u64 v[4:5], v[4:5], 0, s[22:23]
	v_lshl_add_u64 v[0:1], s[12:13], 0, v[0:1]
	v_lshl_add_u64 v[104:105], v[4:5], 0, v[100:101]
	v_mad_u64_u32 v[106:107], s[12:13], v0, s33, v[96:97]
	v_mad_i32_i24 v107, v1, s33, v107
	global_load_dwordx4 v[80:83], v[104:105], off
	global_load_dwordx4 v[84:87], v[106:107], off
	s_mov_b64 s[98:99], 0x20000
	v_lshl_add_u64 v[178:179], v[104:105], 0, s[98:99]
	global_load_dwordx4 v[170:173], v[178:179], off
	global_load_dwordx4 v[174:177], v[106:107], off offset:128
	v_med3_u32 v0, s49, 1, 25
	v_readlane_b32 s73, v239, 33
	v_readfirstlane_b32 s50, v0
	v_readlane_b32 s78, v239, 38
	v_readlane_b32 s79, v239, 39
	s_waitcnt vmcnt(63) expcnt(7) lgkmcnt(15)
	s_barrier
	s_and_saveexec_b64 s[12:13], s[0:1]
	s_cbranch_execz .LBB0_1082
	s_mov_b64 s[38:39], -1
	v_mov_b32_e32 v0, v90
	s_and_saveexec_b64 s[30:31], s[2:3]
	s_cbranch_execz .LBB0_1079
	s_mulk_i32 s40, 0x744
	s_add_u32 s38, s56, s40
	s_addc_u32 s39, s57, 0
	v_mov_b32_e32 v5, 0
	v_mov_b64_e32 v[0:1], v[90:91]
	s_and_saveexec_b64 s[40:41], s[4:5]
	s_cbranch_execz .LBB0_1075
	s_mov_b32 s22, 0
	s_mov_b64 s[42:43], 0
	v_mov_b32_e32 v3, v127
	v_mov_b32_e32 v4, v126
	v_mov_b64_e32 v[0:1], v[90:91]

.LBB0_1084:
	s_bitcmp1_b32 s41, 0
	s_cselect_b32 s40, 0x4200, 0
	s_add_i32 s39, s41, 1
	v_add3_u32 v32, s40, v111, v112
	v_add_u32_e32 v178, s40, v110
	v_add3_u32 v178, v178, v94, s34
	s_cmp_ge_i32 s39, s38
	s_cselect_b64 s[30:31], -1, 0
	s_cbranch_scc1 .Lna_last
	s_waitcnt vmcnt(2)
	s_branch .Lna_w

.Lna_w:
	s_bitcmp1_b32 s41, 0
	s_cbranch_scc1 .Lna_wodd
	ds_write_b128 v32, v[80:83]
	ds_write2_b64 v178, v[84:85], v[86:87] offset1:1
	s_branch .Lna_wd
.Lna_wodd:
	ds_write_b128 v32, v[170:173]
	ds_write2_b64 v178, v[174:175], v[176:177] offset1:1
.Lna_wd:
	s_and_b64 vcc, exec, s[30:31]
	s_waitcnt lgkmcnt(0)
	s_barrier
	s_add_i32 s98, s41, 2
	s_cmp_ge_i32 s98, s38
	s_cbranch_scc1 .LBB0_1086
	s_cmp_gt_u32 s41, 1
	s_cselect_b32 s12, s22, 0
	s_add_i32 s12, s12, s41
	s_lshl_b32 s12, s12, 6
	s_add_i32 s12, s12, 0x80
	s_ashr_i32 s13, s12, 31
	s_lshl_b64 s[42:43], s[12:13], 11
	v_lshl_add_u64 v[32:33], v[104:105], 0, s[42:43]
	v_lshl_add_u64 v[178:179], s[12:13], 1, v[106:107]
	s_bitcmp1_b32 s41, 0
	s_cbranch_scc1 .Lna_lodd
	global_load_dwordx4 v[80:83], v[32:33], off
	global_load_dwordx4 v[84:87], v[178:179], off
	s_branch .LBB0_1086
.Lna_lodd:
	global_load_dwordx4 v[170:173], v[32:33], off
	global_load_dwordx4 v[174:177], v[178:179], off
